# mix_b sample hgrn_local: the 32 serialized state load-fma-store round trips batched (32 loads up front, counted vmcnt waits)
# speedup vs baseline: 1.0118x; 1.0044x over previous
.LBB0_1278:
	s_add_i32 s1, s15, s16
	v_mov_b32_e32 v18, s1
	v_mad_u32_u24 v18, v34, s31, v18
	ds_write_b128 v18, v[14:17] offset:9216
	ds_write_b128 v18, v[10:13] offset:9232
	ds_write_b128 v18, v[6:9] offset:9248
	ds_write_b128 v18, v[2:5] offset:9264
	v_lshrrev_b32_e32 v2, 1, v0
	v_and_b32_e32 v40, 24, v2
	v_bfe_u32 v2, v0, 2, 2
	v_or_b32_e32 v6, v40, v2
	v_lshlrev_b32_e32 v2, 3, v0
	v_and_b32_e32 v7, 24, v2
	v_lshlrev_b32_e32 v2, 1, v0
	v_and_b32_e32 v3, 3, v0
	v_and_or_b32 v2, v2, 24, v3
	v_and_b32_e32 v3, 48, v0
	v_mul_u32_u24_e32 v2, 0x90, v2
	v_mul_u32_u24_e32 v6, 0x90, v6
	v_add3_u32 v38, s15, v3, v2
	v_add3_u32 v39, s1, v7, v6
	s_waitcnt lgkmcnt(0)
	s_barrier
	ds_read_b128 v[2:5], v38 offset:9216
	ds_read_b64_tr_b16 v[8:9], v39 offset:576
	ds_read_b64_tr_b16 v[6:7], v39
	ds_read_b128 v[14:17], v38 offset:9792
	ds_read_b128 v[22:25], v38 offset:13824
	ds_read_b128 v[30:33], v38 offset:14400
	ds_read_b64_tr_b16 v[36:37], v39 offset:608
	ds_read_b64_tr_b16 v[34:35], v39 offset:32
	ds_read_b128 v[54:57], v38 offset:9280
	s_waitcnt lgkmcnt(4)
	v_mfma_f32_16x16x32_bf16 v[26:29], v[22:25], v[6:9], 0
	v_and_b32_e32 v41, 15, v0
	s_mov_b64 s[8:9], -1
	s_and_b64 vcc, exec, s[6:7]
	s_waitcnt lgkmcnt(1)
	v_mfma_f32_16x16x32_bf16 v[50:53], v[22:25], v[34:37], 0
	ds_read_b64_tr_b16 v[22:23], v39 offset:4608
	ds_read_b64_tr_b16 v[24:25], v39 offset:5184
	ds_read_b128 v[58:61], v38 offset:9856
	v_mfma_f32_16x16x32_bf16 v[10:13], v[2:5], v[6:9], 0
	v_mfma_f32_16x16x32_bf16 v[18:21], v[14:17], v[6:9], 0
	v_mfma_f32_16x16x32_bf16 v[46:49], v[2:5], v[34:37], 0
	s_waitcnt lgkmcnt(1)
	v_mfma_f32_16x16x32_bf16 v[2:5], v[54:57], v[22:25], v[10:13]
	s_waitcnt lgkmcnt(0)
	v_mfma_f32_16x16x32_bf16 v[10:13], v[58:61], v[22:25], v[18:21]
	s_nop 2
	ds_read_b128 v[18:21], v38 offset:13888
	ds_read_b128 v[62:65], v38 offset:14464
	ds_read_b64_tr_b16 v[68:69], v39 offset:5216
	ds_read_b64_tr_b16 v[66:67], v39 offset:4640
	v_mfma_f32_16x16x32_bf16 v[42:45], v[30:33], v[6:9], 0
	v_mfma_f32_16x16x32_bf16 v[14:17], v[14:17], v[34:37], 0
	v_mfma_f32_16x16x32_bf16 v[34:37], v[30:33], v[34:37], 0
	s_waitcnt lgkmcnt(3)
	v_mfma_f32_16x16x32_bf16 v[6:9], v[18:21], v[22:25], v[26:29]
	s_waitcnt lgkmcnt(2)
	v_mfma_f32_16x16x32_bf16 v[22:25], v[62:65], v[22:25], v[42:45]
	s_waitcnt lgkmcnt(0)
	v_mfma_f32_16x16x32_bf16 v[30:33], v[54:57], v[66:69], v[46:49]
	v_mfma_f32_16x16x32_bf16 v[26:29], v[58:61], v[66:69], v[14:17]
	v_mfma_f32_16x16x32_bf16 v[18:21], v[18:21], v[66:69], v[50:53]
	v_mfma_f32_16x16x32_bf16 v[14:17], v[62:65], v[66:69], v[34:37]
	s_cbranch_vccz .LBB0_1280
	s_add_i32 s6, s12, s10
	s_mov_b32 s7, s68
	s_ashr_i32 s1, s0, 31
	s_lshl_b64 s[6:7], s[6:7], 14
	s_lshl_b64 s[8:9], s[0:1], 12
	s_add_u32 s6, s8, s6
	s_addc_u32 s7, s9, s7
	s_lshl_b32 s1, s17, 2
	s_add_i32 s1, s1, 0
	s_add_i32 s1, s1, 0x1b000
	s_lshl_b64 s[8:9], s[6:7], 2
	s_add_u32 s6, s22, s8
	s_addc_u32 s7, s23, s9
	v_lshlrev_b32_e32 v0, 8, v40
	v_lshlrev_b32_e32 v38, 2, v41
	v_lshl_add_u64 v[44:45], s[6:7], 0, v[0:1]
	v_lshl_or_b32 v38, s14, 7, v38
	v_mov_b32_e32 v39, v1
	v_lshl_add_u64 v[44:45], v[44:45], 0, v[38:39]
	v_lshl_add_u32 v42, v40, 2, s1
	s_add_u32 s5, s56, s8
	s_addc_u32 s9, s57, s9
	s_add_u32 s8, s5, 0x10780000
	s_addc_u32 s9, s9, 0
	ds_read_b128 v[50:53], v42 offset:2048
	ds_read_b128 v[58:61], v42 offset:2064
	ds_read_b128 v[130:133], v42 offset:2176
	ds_read_b128 v[212:215], v42 offset:2192
	v_lshl_add_u64 v[46:47], s[8:9], 0, v[0:1]
	v_lshl_add_u64 v[46:47], v[46:47], 0, v[38:39]
	s_mov_b64 s[8:9], 0x2000
	v_lshl_add_u64 v[216:217], v[44:45], 0, s[8:9]
	v_lshl_add_u64 v[218:219], v[46:47], 0, s[8:9]
	global_load_dword v98, v[44:45], off
	global_load_dword v99, v[44:45], off offset:64
	global_load_dword v100, v[44:45], off offset:256
	global_load_dword v101, v[44:45], off offset:320
	global_load_dword v102, v[44:45], off offset:512
	global_load_dword v103, v[44:45], off offset:576
	global_load_dword v104, v[44:45], off offset:768
	global_load_dword v105, v[44:45], off offset:832
	global_load_dword v106, v[44:45], off offset:1024
	global_load_dword v107, v[44:45], off offset:1088
	global_load_dword v108, v[44:45], off offset:1280
	global_load_dword v109, v[44:45], off offset:1344
	global_load_dword v110, v[44:45], off offset:1536
	global_load_dword v111, v[44:45], off offset:1600
	global_load_dword v112, v[44:45], off offset:1792
	global_load_dword v113, v[44:45], off offset:1856
	global_load_dword v114, v[216:217], off
	global_load_dword v115, v[216:217], off offset:64
	global_load_dword v116, v[216:217], off offset:256
	global_load_dword v117, v[216:217], off offset:320
	global_load_dword v118, v[216:217], off offset:512
	global_load_dword v119, v[216:217], off offset:576
	global_load_dword v120, v[216:217], off offset:768
	global_load_dword v121, v[216:217], off offset:832
	global_load_dword v122, v[216:217], off offset:1024
	global_load_dword v123, v[216:217], off offset:1088
	global_load_dword v124, v[216:217], off offset:1280
	global_load_dword v125, v[216:217], off offset:1344
	global_load_dword v126, v[216:217], off offset:1536
	global_load_dword v127, v[216:217], off offset:1600
	global_load_dword v128, v[216:217], off offset:1792
	global_load_dword v129, v[216:217], off offset:1856
	s_waitcnt lgkmcnt(0)
	s_waitcnt vmcnt(31)
	v_fma_f32 v98, v50, v98, v2
	global_store_dword v[46:47], v98, off
	s_waitcnt vmcnt(31)
	v_fma_f32 v99, v50, v99, v30
	global_store_dword v[46:47], v99, off offset:64
	s_waitcnt vmcnt(31)
	v_fma_f32 v100, v51, v100, v3
	global_store_dword v[46:47], v100, off offset:256
	s_waitcnt vmcnt(31)
	v_fma_f32 v101, v51, v101, v31
	global_store_dword v[46:47], v101, off offset:320
	s_waitcnt vmcnt(31)
	v_fma_f32 v102, v52, v102, v4
	global_store_dword v[46:47], v102, off offset:512
	s_waitcnt vmcnt(31)
	v_fma_f32 v103, v52, v103, v32
	global_store_dword v[46:47], v103, off offset:576
	s_waitcnt vmcnt(31)
	v_fma_f32 v104, v53, v104, v5
	global_store_dword v[46:47], v104, off offset:768
	s_waitcnt vmcnt(31)
	v_fma_f32 v105, v53, v105, v33
	global_store_dword v[46:47], v105, off offset:832
	s_waitcnt vmcnt(31)
	v_fma_f32 v106, v58, v106, v10
	global_store_dword v[46:47], v106, off offset:1024
	s_waitcnt vmcnt(31)
	v_fma_f32 v107, v58, v107, v26
	global_store_dword v[46:47], v107, off offset:1088
	s_waitcnt vmcnt(31)
	v_fma_f32 v108, v59, v108, v11
	global_store_dword v[46:47], v108, off offset:1280
	s_waitcnt vmcnt(31)
	v_fma_f32 v109, v59, v109, v27
	global_store_dword v[46:47], v109, off offset:1344
	s_waitcnt vmcnt(31)
	v_fma_f32 v110, v60, v110, v12
	global_store_dword v[46:47], v110, off offset:1536
	s_waitcnt vmcnt(31)
	v_fma_f32 v111, v60, v111, v28
	global_store_dword v[46:47], v111, off offset:1600
	s_waitcnt vmcnt(31)
	v_fma_f32 v112, v61, v112, v13
	global_store_dword v[46:47], v112, off offset:1792
	s_waitcnt vmcnt(31)
	v_fma_f32 v113, v61, v113, v29
	global_store_dword v[46:47], v113, off offset:1856
	s_waitcnt vmcnt(31)
	v_fma_f32 v114, v130, v114, v6
	global_store_dword v[218:219], v114, off
	s_waitcnt vmcnt(31)
	v_fma_f32 v115, v130, v115, v18
	global_store_dword v[218:219], v115, off offset:64
	s_waitcnt vmcnt(31)
	v_fma_f32 v116, v131, v116, v7
	global_store_dword v[218:219], v116, off offset:256
	s_waitcnt vmcnt(31)
	v_fma_f32 v117, v131, v117, v19
	global_store_dword v[218:219], v117, off offset:320
	s_waitcnt vmcnt(31)
	v_fma_f32 v118, v132, v118, v8
	global_store_dword v[218:219], v118, off offset:512
	s_waitcnt vmcnt(31)
	v_fma_f32 v119, v132, v119, v20
	global_store_dword v[218:219], v119, off offset:576
	s_waitcnt vmcnt(31)
	v_fma_f32 v120, v133, v120, v9
	global_store_dword v[218:219], v120, off offset:768
	s_waitcnt vmcnt(31)
	v_fma_f32 v121, v133, v121, v21
	global_store_dword v[218:219], v121, off offset:832
	s_waitcnt vmcnt(31)
	v_fma_f32 v122, v212, v122, v22
	global_store_dword v[218:219], v122, off offset:1024
	s_waitcnt vmcnt(31)
	v_fma_f32 v123, v212, v123, v14
	global_store_dword v[218:219], v123, off offset:1088
	s_waitcnt vmcnt(31)
	v_fma_f32 v124, v213, v124, v23
	global_store_dword v[218:219], v124, off offset:1280
	s_waitcnt vmcnt(31)
	v_fma_f32 v125, v213, v125, v15
	global_store_dword v[218:219], v125, off offset:1344
	s_waitcnt vmcnt(31)
	v_fma_f32 v126, v214, v126, v24
	global_store_dword v[218:219], v126, off offset:1536
	s_waitcnt vmcnt(31)
	v_fma_f32 v127, v214, v127, v16
	global_store_dword v[218:219], v127, off offset:1600
	s_waitcnt vmcnt(31)
	v_fma_f32 v128, v215, v128, v25
	global_store_dword v[218:219], v128, off offset:1792
	s_waitcnt vmcnt(31)
	v_fma_f32 v129, v215, v129, v17
	global_store_dword v[218:219], v129, off offset:1856
	s_mov_b64 s[8:9], 0
